# scan O stores write-through (sc1) on the counted-wait fast path: the B3 release has less to write back
# baseline (speedup 1.0000x reference)
; #define LAS __attribute__((address_space(3)))
; __device__ __forceinline__ unsigned pk2(float lo, float hi) { const f32x2_t v = {lo, hi}; const bf16x2_t b = __builtin_convertvector(v, bf16x2_t); return __builtin_bit_cast(unsigned, b); }
; __device__ __forceinline__ bf16x8 cat8(const s16x4 a, const s16x4 b) { return __builtin_shufflevector(a, b, 0, 1, 2, 3, 4, 5, 6, 7); }
; __device__ __forceinline__ void hgrn_scan(const Params& p, LAS unsigned char* lds, int chain) {
;     ...
;         if (lat) {
;             bf16x8 sb[4];
; #pragma unroll
;             for (int ks = 0; ks < 4; ++ks) sb[ks] = pack_p(S[2 * ks], S[2 * ks + 1]);
;             bf16* orow = O + (long)hg_row(dir, b, 64 * c) * WA;
; #pragma unroll
;             for (int I = 0; I < 4; ++I) {
;                 f32x4 o = (f32x4){0.f, 0.f, 0.f, 0.f};
; #pragma unroll
;                 for (int ks = 0; ks < 4; ++ks) {
;                     const LAS unsigned char* ap = bb + SB_QD + (32 * ks + 4 * g + qq) * HP + (16 * I + 4 * pp) * 2;
;                     o = __builtin_amdgcn_mfma_f32_16x16x32_bf16(sb[ks], cat8(lds_tr(ap), lds_tr(ap + 16 * HP)), o, 0, 0, 0);
;                 }
; #pragma unroll
;                 for (int sp = 0; sp < 2; ++sp) {
;                     if (2 * sp > I) break;
;                     const LAS unsigned char* pr = bb + SB_P + (16 * I + li) * PP + (32 * sp + 4 * g) * 2;
;                     const u32x2 lo = *(const LAS u32x2*)pr; u32x2 hi = (u32x2){0u, 0u};
;                     if (2 * sp + 1 <= I) hi = *(const LAS u32x2*)(pr + 32);
;                     o = __builtin_amdgcn_mfma_f32_16x16x32_bf16(vf[sp], cat8u(lo, hi), o, 0, 0, 0);
;                 }
;                 { u32x2 w; w.x = pk2(o.x, o.y); w.y = pk2(o.z, o.w); *(u32x2*)(orow + (long)(16 * I + li) * ost) = w; }
;             }
.LBB0_410:
	s_andn2_b64 vcc, exec, s[18:19]
	s_cbranch_vccnz .LBB0_412
	v_cvt_pk_bf16_f32 v104, v76, v77
	v_cvt_pk_bf16_f32 v105, v78, v79
	v_cvt_pk_bf16_f32 v106, v92, v93
	v_cvt_pk_bf16_f32 v107, v94, v95
	v_add_u32_e32 v165, v139, v141
	v_cvt_pk_bf16_f32 v108, v80, v81
	v_cvt_pk_bf16_f32 v109, v82, v83
	v_cvt_pk_bf16_f32 v110, v88, v89
	v_cvt_pk_bf16_f32 v111, v90, v91
	ds_read_b64_tr_b16 v[176:177], v165 offset:2560
	ds_read_b64_tr_b16 v[174:175], v165
	ds_read_b64_tr_b16 v[178:179], v165 offset:32
	ds_read_b64_tr_b16 v[182:183], v165 offset:64
	ds_read_b64_tr_b16 v[186:187], v165 offset:96
	ds_read_b64_tr_b16 v[180:181], v165 offset:2592
	ds_read_b64_tr_b16 v[184:185], v165 offset:2624
	ds_read_b64_tr_b16 v[188:189], v165 offset:2656
	s_waitcnt lgkmcnt(6)
	v_mfma_f32_16x16x32_bf16 v[174:177], v[104:107], v[174:177], 0
	v_cvt_pk_bf16_f32 v166, v72, v73
	v_cvt_pk_bf16_f32 v167, v74, v75
	v_cvt_pk_bf16_f32 v168, v84, v85
	s_waitcnt lgkmcnt(2)
	v_mfma_f32_16x16x32_bf16 v[178:181], v[104:107], v[178:181], 0
	v_cvt_pk_bf16_f32 v169, v86, v87
	ds_read_b64_tr_b16 v[192:193], v165 offset:7680
	ds_read_b64_tr_b16 v[190:191], v165 offset:5120
	ds_read_b64_tr_b16 v[194:195], v165 offset:5152
	ds_read_b64_tr_b16 v[198:199], v165 offset:5184
	ds_read_b64_tr_b16 v[202:203], v165 offset:5216
	ds_read_b64_tr_b16 v[196:197], v165 offset:7712
	ds_read_b64_tr_b16 v[200:201], v165 offset:7744
	ds_read_b64_tr_b16 v[204:205], v165 offset:7776
	v_cvt_pk_bf16_f32 v170, v64, v65
	s_waitcnt lgkmcnt(6)
	v_mfma_f32_16x16x32_bf16 v[174:177], v[108:111], v[190:193], v[174:177]
	ds_read_b64_tr_b16 v[192:193], v165 offset:12800
	ds_read_b64_tr_b16 v[190:191], v165 offset:10240
	ds_read_b64_tr_b16 v[206:207], v165 offset:10272
	ds_read_b64_tr_b16 v[210:211], v165 offset:10304
	ds_read_b64_tr_b16 v[214:215], v165 offset:10336
	ds_read_b64_tr_b16 v[208:209], v165 offset:12832
	ds_read_b64_tr_b16 v[212:213], v165 offset:12864
	ds_read_b64_tr_b16 v[216:217], v165 offset:12896
	v_cvt_pk_bf16_f32 v171, v66, v67
	v_cvt_pk_bf16_f32 v172, v68, v69
	s_waitcnt lgkmcnt(10)
	v_mfma_f32_16x16x32_bf16 v[178:181], v[108:111], v[194:197], v[178:181]
	v_cvt_pk_bf16_f32 v173, v70, v71
	v_add_u32_e32 v234, v140, v142
	v_mov_b32_e32 v220, v115
	v_mfma_f32_16x16x32_bf16 v[182:185], v[104:107], v[182:185], 0
	v_mov_b32_e32 v221, v115
	s_and_b64 s[18:19], s[6:7], exec
	s_cselect_b32 s12, s22, s20
	s_waitcnt lgkmcnt(6)
	v_mfma_f32_16x16x32_bf16 v[174:177], v[166:169], v[190:193], v[174:177]
	ds_read_b64_tr_b16 v[192:193], v165 offset:17920
	ds_read_b64 v[218:219], v234 offset:40960
	ds_read_b64_tr_b16 v[190:191], v165 offset:15360
	ds_read_b64_tr_b16 v[222:223], v165 offset:15392
	ds_read_b64_tr_b16 v[226:227], v165 offset:15424
	ds_read_b64_tr_b16 v[230:231], v165 offset:15456
	ds_read_b64_tr_b16 v[224:225], v165 offset:17952
	ds_read_b64_tr_b16 v[228:229], v165 offset:17984
	ds_read_b64_tr_b16 v[232:233], v165 offset:18016
	v_add_u32_e32 v165, 0xa800, v234
	s_waitcnt lgkmcnt(11)
	v_mfma_f32_16x16x32_bf16 v[178:181], v[166:169], v[206:209], v[178:181]
	s_lshl_b64 s[18:19], s[12:13], 11
	v_mfma_f32_16x16x32_bf16 v[182:185], v[108:111], v[198:201], v[182:185]
	s_waitcnt lgkmcnt(6)
	v_mfma_f32_16x16x32_bf16 v[174:177], v[170:173], v[190:193], v[174:177]
	ds_read2_b64 v[192:195], v165 offset0:32 offset1:36
	v_add_u32_e32 v165, 0xb000, v234
	ds_read_b64 v[190:191], v234 offset:45632
	s_waitcnt lgkmcnt(4)
	v_mfma_f32_16x16x32_bf16 v[178:181], v[170:173], v[222:225], v[178:181]
	v_mfma_f32_16x16x32_bf16 v[182:185], v[166:169], v[210:213], v[182:185]
	v_mfma_f32_16x16x32_bf16 v[104:107], v[104:107], v[186:189], 0
	s_waitcnt lgkmcnt(1)
	v_mfma_f32_16x16x32_bf16 v[178:181], v[100:103], v[192:195], v[178:181]
	ds_read2_b64 v[192:195], v165 offset0:64 offset1:68
	v_add_u32_e32 v165, 0xb800, v234
	v_mfma_f32_16x16x32_bf16 v[182:185], v[170:173], v[226:229], v[182:185]
	v_mfma_f32_16x16x32_bf16 v[104:107], v[108:111], v[202:205], v[104:107]
	ds_read2_b64 v[108:111], v165 offset0:96 offset1:100
	s_waitcnt lgkmcnt(1)
	v_mfma_f32_16x16x32_bf16 v[182:185], v[100:103], v[192:195], v[182:185]
	v_mov_b32_e32 v192, v115
	v_mov_b32_e32 v193, v115
	v_mfma_f32_16x16x32_bf16 v[104:107], v[166:169], v[214:217], v[104:107]
	v_mfma_f32_16x16x32_bf16 v[174:177], v[100:103], v[218:221], v[174:177]
	v_mfma_f32_16x16x32_bf16 v[182:185], v[96:99], v[190:193], v[182:185]
	v_lshl_add_u64 v[190:191], v[118:119], 0, s[18:19]
	s_nop 5
	v_cvt_pk_bf16_f32 v174, v174, v175
	v_cvt_pk_bf16_f32 v175, v176, v177
	v_mfma_f32_16x16x32_bf16 v[104:107], v[170:173], v[230:233], v[104:107]
	v_lshl_add_u64 v[176:177], v[120:121], 1, v[190:191]
	global_store_dwordx2 v[176:177], v[174:175], off sc1
	v_cvt_pk_bf16_f32 v174, v178, v179
	v_cvt_pk_bf16_f32 v175, v180, v181
	v_lshl_add_u64 v[166:167], v[122:123], 1, v[190:191]
	global_store_dwordx2 v[166:167], v[174:175], off sc1
	ds_read2_b64 v[166:169], v165 offset0:104 offset1:108
	s_waitcnt lgkmcnt(1)
	v_mfma_f32_16x16x32_bf16 v[104:107], v[100:103], v[108:111], v[104:107]
	v_cvt_pk_bf16_f32 v170, v182, v183
	v_cvt_pk_bf16_f32 v171, v184, v185
	v_lshl_add_u64 v[108:109], v[124:125], 1, v[190:191]
	s_waitcnt lgkmcnt(0)
	v_mfma_f32_16x16x32_bf16 v[104:107], v[96:99], v[166:169], v[104:107]
	global_store_dwordx2 v[108:109], v[170:171], off sc1
	s_nop 6
	v_cvt_pk_bf16_f32 v104, v104, v105
	v_cvt_pk_bf16_f32 v105, v106, v107
	v_lshl_add_u64 v[106:107], v[126:127], 1, v[190:191]
	global_store_dwordx2 v[106:107], v[104:105], off sc1

; #define LAS __attribute__((address_space(3)))
; __device__ __forceinline__ unsigned pk2(float lo, float hi) { const f32x2_t v = {lo, hi}; const bf16x2_t b = __builtin_convertvector(v, bf16x2_t); return __builtin_bit_cast(unsigned, b); }
; __device__ __forceinline__ bf16x8 cat8(const s16x4 a, const s16x4 b) { return __builtin_shufflevector(a, b, 0, 1, 2, 3, 4, 5, 6, 7); }
; __device__ __forceinline__ void hgrn_scan(const Params& p, LAS unsigned char* lds, int chain) {
;     ...
;         if (lat) {
;             bf16x8 sb[4];
; #pragma unroll
;             for (int ks = 0; ks < 4; ++ks) sb[ks] = pack_p(S[2 * ks], S[2 * ks + 1]);
;             bf16* orow = O + (long)hg_row(dir, b, 64 * c) * WA;
; #pragma unroll
;             for (int I = 0; I < 4; ++I) {
;                 f32x4 o = (f32x4){0.f, 0.f, 0.f, 0.f};
; #pragma unroll
;                 for (int ks = 0; ks < 4; ++ks) {
;                     const LAS unsigned char* ap = bb + SB_QD + (32 * ks + 4 * g + qq) * HP + (16 * I + 4 * pp) * 2;
;                     o = __builtin_amdgcn_mfma_f32_16x16x32_bf16(sb[ks], cat8(lds_tr(ap), lds_tr(ap + 16 * HP)), o, 0, 0, 0);
;                 }
; #pragma unroll
;                 for (int sp = 0; sp < 2; ++sp) {
;                     if (2 * sp > I) break;
;                     const LAS unsigned char* pr = bb + SB_P + (16 * I + li) * PP + (32 * sp + 4 * g) * 2;
;                     const u32x2 lo = *(const LAS u32x2*)pr; u32x2 hi = (u32x2){0u, 0u};
;                     if (2 * sp + 1 <= I) hi = *(const LAS u32x2*)(pr + 32);
;                     o = __builtin_amdgcn_mfma_f32_16x16x32_bf16(vf[sp], cat8u(lo, hi), o, 0, 0, 0);
;                 }
;                 { u32x2 w; w.x = pk2(o.x, o.y); w.y = pk2(o.z, o.w); *(u32x2*)(orow + (long)(16 * I + li) * ost) = w; }
;             }
.LBB0_424:
	s_andn2_b64 vcc, exec, s[16:17]
	s_cbranch_vccnz .LBB0_426
	v_cvt_pk_bf16_f32 v104, v76, v77
	v_cvt_pk_bf16_f32 v105, v78, v79
	v_cvt_pk_bf16_f32 v106, v92, v93
	v_cvt_pk_bf16_f32 v107, v94, v95
	ds_read_b64_tr_b16 v[176:177], v162 offset:2560
	ds_read_b64_tr_b16 v[174:175], v162
	ds_read_b64_tr_b16 v[178:179], v162 offset:32
	ds_read_b64_tr_b16 v[182:183], v162 offset:64
	ds_read_b64_tr_b16 v[186:187], v162 offset:96
	ds_read_b64_tr_b16 v[180:181], v162 offset:2592
	ds_read_b64_tr_b16 v[184:185], v162 offset:2624
	ds_read_b64_tr_b16 v[188:189], v162 offset:2656
	v_cvt_pk_bf16_f32 v108, v80, v81
	v_cvt_pk_bf16_f32 v109, v82, v83
	v_cvt_pk_bf16_f32 v110, v88, v89
	v_cvt_pk_bf16_f32 v111, v90, v91
	s_waitcnt lgkmcnt(6)
	v_mfma_f32_16x16x32_bf16 v[174:177], v[104:107], v[174:177], 0
	ds_read_b64_tr_b16 v[192:193], v162 offset:7680
	ds_read_b64_tr_b16 v[190:191], v162 offset:5120
	ds_read_b64_tr_b16 v[194:195], v162 offset:5152
	ds_read_b64_tr_b16 v[198:199], v162 offset:5184
	ds_read_b64_tr_b16 v[202:203], v162 offset:5216
	ds_read_b64_tr_b16 v[196:197], v162 offset:7712
	ds_read_b64_tr_b16 v[200:201], v162 offset:7744
	ds_read_b64_tr_b16 v[204:205], v162 offset:7776
	v_cvt_pk_bf16_f32 v166, v72, v73
	v_cvt_pk_bf16_f32 v167, v74, v75
	s_waitcnt lgkmcnt(10)
	v_mfma_f32_16x16x32_bf16 v[178:181], v[104:107], v[178:181], 0
	v_cvt_pk_bf16_f32 v168, v84, v85
	v_cvt_pk_bf16_f32 v169, v86, v87
	v_cvt_pk_bf16_f32 v170, v64, v65
	s_waitcnt lgkmcnt(6)
	v_mfma_f32_16x16x32_bf16 v[174:177], v[108:111], v[190:193], v[174:177]
	ds_read_b64_tr_b16 v[192:193], v162 offset:12800
	ds_read_b64_tr_b16 v[190:191], v162 offset:10240
	ds_read_b64_tr_b16 v[206:207], v162 offset:10272
	ds_read_b64_tr_b16 v[210:211], v162 offset:10304
	ds_read_b64_tr_b16 v[214:215], v162 offset:10336
	ds_read_b64_tr_b16 v[208:209], v162 offset:12832
	ds_read_b64_tr_b16 v[212:213], v162 offset:12864
	ds_read_b64_tr_b16 v[216:217], v162 offset:12896
	v_cvt_pk_bf16_f32 v171, v66, v67
	v_cvt_pk_bf16_f32 v172, v68, v69
	s_waitcnt lgkmcnt(10)
	v_mfma_f32_16x16x32_bf16 v[178:181], v[108:111], v[194:197], v[178:181]
	v_cvt_pk_bf16_f32 v173, v70, v71
	v_add_u32_e32 v165, 0x800, v163
	v_mov_b32_e32 v220, v115
	v_mfma_f32_16x16x32_bf16 v[182:185], v[104:107], v[182:185], 0
	v_mov_b32_e32 v221, v115
	s_add_i32 s12, s22, 64
	s_sub_i32 s18, s20, 64
	s_waitcnt lgkmcnt(6)
	v_mfma_f32_16x16x32_bf16 v[174:177], v[166:169], v[190:193], v[174:177]
	ds_read_b64_tr_b16 v[192:193], v162 offset:17920
	ds_read_b64 v[218:219], v163
	ds_read_b64_tr_b16 v[190:191], v162 offset:15360
	ds_read_b64_tr_b16 v[222:223], v162 offset:15392
	ds_read_b64_tr_b16 v[226:227], v162 offset:15424
	ds_read_b64_tr_b16 v[230:231], v162 offset:15456
	ds_read_b64_tr_b16 v[224:225], v162 offset:17952
	ds_read_b64_tr_b16 v[228:229], v162 offset:17984
	ds_read_b64_tr_b16 v[232:233], v162 offset:18016
	s_and_b64 s[16:17], s[6:7], exec
	s_cselect_b32 s12, s12, s18
	s_waitcnt lgkmcnt(11)
	v_mfma_f32_16x16x32_bf16 v[178:181], v[166:169], v[206:209], v[178:181]
	s_lshl_b64 s[16:17], s[12:13], 11
	v_mfma_f32_16x16x32_bf16 v[182:185], v[108:111], v[198:201], v[182:185]
	s_waitcnt lgkmcnt(6)
	v_mfma_f32_16x16x32_bf16 v[174:177], v[170:173], v[190:193], v[174:177]
	ds_read2_b64 v[192:195], v165 offset0:32 offset1:36
	v_add_u32_e32 v165, 0x1000, v163
	ds_read_b64 v[190:191], v163 offset:4672
	s_waitcnt lgkmcnt(4)
	v_mfma_f32_16x16x32_bf16 v[178:181], v[170:173], v[222:225], v[178:181]
	v_mfma_f32_16x16x32_bf16 v[182:185], v[166:169], v[210:213], v[182:185]
	v_mfma_f32_16x16x32_bf16 v[104:107], v[104:107], v[186:189], 0
	s_waitcnt lgkmcnt(1)
	v_mfma_f32_16x16x32_bf16 v[178:181], v[100:103], v[192:195], v[178:181]
	ds_read2_b64 v[192:195], v165 offset0:64 offset1:68
	v_add_u32_e32 v165, 0x1800, v163
	v_mfma_f32_16x16x32_bf16 v[182:185], v[170:173], v[226:229], v[182:185]
	v_mfma_f32_16x16x32_bf16 v[104:107], v[108:111], v[202:205], v[104:107]
	ds_read2_b64 v[108:111], v165 offset0:96 offset1:100
	s_waitcnt lgkmcnt(1)
	v_mfma_f32_16x16x32_bf16 v[182:185], v[100:103], v[192:195], v[182:185]
	v_mov_b32_e32 v192, v115
	v_mov_b32_e32 v193, v115
	v_mfma_f32_16x16x32_bf16 v[104:107], v[166:169], v[214:217], v[104:107]
	v_mfma_f32_16x16x32_bf16 v[174:177], v[100:103], v[218:221], v[174:177]
	v_mfma_f32_16x16x32_bf16 v[182:185], v[96:99], v[190:193], v[182:185]
	v_lshl_add_u64 v[190:191], v[118:119], 0, s[16:17]
	s_nop 5
	v_cvt_pk_bf16_f32 v174, v174, v175
	v_cvt_pk_bf16_f32 v175, v176, v177
	v_mfma_f32_16x16x32_bf16 v[104:107], v[170:173], v[230:233], v[104:107]
	v_lshl_add_u64 v[176:177], v[120:121], 1, v[190:191]
	global_store_dwordx2 v[176:177], v[174:175], off sc1
	v_cvt_pk_bf16_f32 v174, v178, v179
	v_cvt_pk_bf16_f32 v175, v180, v181
	v_lshl_add_u64 v[166:167], v[122:123], 1, v[190:191]
	global_store_dwordx2 v[166:167], v[174:175], off sc1
	ds_read2_b64 v[166:169], v165 offset0:104 offset1:108
	s_waitcnt lgkmcnt(1)
	v_mfma_f32_16x16x32_bf16 v[104:107], v[100:103], v[108:111], v[104:107]
	v_cvt_pk_bf16_f32 v170, v182, v183
	v_cvt_pk_bf16_f32 v171, v184, v185
	v_lshl_add_u64 v[108:109], v[124:125], 1, v[190:191]
	s_waitcnt lgkmcnt(0)
	v_mfma_f32_16x16x32_bf16 v[104:107], v[96:99], v[166:169], v[104:107]
	global_store_dwordx2 v[108:109], v[170:171], off sc1
	s_nop 6
	v_cvt_pk_bf16_f32 v104, v104, v105
	v_cvt_pk_bf16_f32 v105, v106, v107
	v_lshl_add_u64 v[106:107], v[126:127], 1, v[190:191]
	global_store_dwordx2 v[106:107], v[104:105], off sc1
